# helper conversion stores write-through too (sc1), on top of sc1 GEMM epilogues, balanced 160-row P3/P7/P10, relocated helper work
# speedup vs baseline: 1.0241x; 1.0013x over previous
.LBB0_181:
	v_add_u32_e32 v18, s1, v16
	v_add_u32_e32 v20, 2, v18
	v_add_u32_e32 v22, 4, v18
	v_add_u32_e32 v24, 6, v18
	v_ashrrev_i32_e32 v19, 31, v18
	v_add_u32_e32 v26, 8, v18
	v_add_u32_e32 v28, 10, v18
	v_add_u32_e32 v30, 12, v18
	v_add_u32_e32 v32, 14, v18
	v_ashrrev_i32_e32 v21, 31, v20
	v_ashrrev_i32_e32 v23, 31, v22
	v_ashrrev_i32_e32 v25, 31, v24
	v_lshlrev_b64 v[18:19], 12, v[18:19]
	v_ashrrev_i32_e32 v27, 31, v26
	v_ashrrev_i32_e32 v29, 31, v28
	v_ashrrev_i32_e32 v31, 31, v30
	v_ashrrev_i32_e32 v33, 31, v32
	v_lshlrev_b64 v[20:21], 12, v[20:21]
	v_lshlrev_b64 v[22:23], 12, v[22:23]
	v_lshlrev_b64 v[24:25], 12, v[24:25]
	v_lshl_add_u64 v[18:19], v[6:7], 0, v[18:19]
	v_lshlrev_b64 v[26:27], 12, v[26:27]
	v_lshlrev_b64 v[28:29], 12, v[28:29]
	v_lshlrev_b64 v[30:31], 12, v[30:31]
	v_lshlrev_b64 v[32:33], 12, v[32:33]
	v_lshl_add_u64 v[20:21], v[6:7], 0, v[20:21]
	v_lshl_add_u64 v[22:23], v[6:7], 0, v[22:23]
	v_lshl_add_u64 v[24:25], v[6:7], 0, v[24:25]
	v_lshl_add_u64 v[26:27], v[6:7], 0, v[26:27]
	v_lshl_add_u64 v[28:29], v[6:7], 0, v[28:29]
	v_lshl_add_u64 v[30:31], v[6:7], 0, v[30:31]
	v_lshl_add_u64 v[32:33], v[6:7], 0, v[32:33]
	global_load_dword v100, v[18:19], off nt
	s_nop 0
	global_load_dword v101, v[20:21], off nt
	s_nop 0
	global_load_dword v102, v[22:23], off nt
	global_load_dword v103, v[24:25], off nt
	s_nop 0
	global_load_dword v104, v[26:27], off nt
	global_load_dword v105, v[28:29], off nt
	global_load_dword v106, v[30:31], off nt
	global_load_dword v107, v[32:33], off nt
	s_add_i32 s1, s1, 16
	v_add_u32_e32 v18, s1, v16
	v_add_u32_e32 v20, 2, v18
	v_add_u32_e32 v22, 4, v18
	v_add_u32_e32 v24, 6, v18
	v_ashrrev_i32_e32 v19, 31, v18
	v_add_u32_e32 v26, 8, v18
	v_add_u32_e32 v28, 10, v18
	v_add_u32_e32 v30, 12, v18
	v_add_u32_e32 v32, 14, v18
	v_ashrrev_i32_e32 v21, 31, v20
	v_ashrrev_i32_e32 v23, 31, v22
	v_ashrrev_i32_e32 v25, 31, v24
	v_lshlrev_b64 v[18:19], 12, v[18:19]
	v_ashrrev_i32_e32 v27, 31, v26
	v_ashrrev_i32_e32 v29, 31, v28
	v_ashrrev_i32_e32 v31, 31, v30
	v_ashrrev_i32_e32 v33, 31, v32
	v_lshlrev_b64 v[20:21], 12, v[20:21]
	v_lshlrev_b64 v[22:23], 12, v[22:23]
	v_lshlrev_b64 v[24:25], 12, v[24:25]
	v_lshl_add_u64 v[18:19], v[6:7], 0, v[18:19]
	v_lshlrev_b64 v[26:27], 12, v[26:27]
	v_lshlrev_b64 v[28:29], 12, v[28:29]
	v_lshlrev_b64 v[30:31], 12, v[30:31]
	v_lshlrev_b64 v[32:33], 12, v[32:33]
	v_lshl_add_u64 v[20:21], v[6:7], 0, v[20:21]
	v_lshl_add_u64 v[22:23], v[6:7], 0, v[22:23]
	v_lshl_add_u64 v[24:25], v[6:7], 0, v[24:25]
	v_lshl_add_u64 v[26:27], v[6:7], 0, v[26:27]
	v_lshl_add_u64 v[28:29], v[6:7], 0, v[28:29]
	v_lshl_add_u64 v[30:31], v[6:7], 0, v[30:31]
	v_lshl_add_u64 v[32:33], v[6:7], 0, v[32:33]
	global_load_dword v108, v[18:19], off nt
	s_nop 0
	global_load_dword v109, v[20:21], off nt
	s_nop 0
	global_load_dword v110, v[22:23], off nt
	global_load_dword v111, v[24:25], off nt
	s_nop 0
	global_load_dword v112, v[26:27], off nt
	global_load_dword v113, v[28:29], off nt
	global_load_dword v114, v[30:31], off nt
	global_load_dword v115, v[32:33], off nt
	s_add_i32 s1, s1, 16
	v_add_u32_e32 v18, s1, v16
	v_add_u32_e32 v20, 2, v18
	v_add_u32_e32 v22, 4, v18
	v_add_u32_e32 v24, 6, v18
	v_ashrrev_i32_e32 v19, 31, v18
	v_add_u32_e32 v26, 8, v18
	v_add_u32_e32 v28, 10, v18
	v_add_u32_e32 v30, 12, v18
	v_add_u32_e32 v32, 14, v18
	v_ashrrev_i32_e32 v21, 31, v20
	v_ashrrev_i32_e32 v23, 31, v22
	v_ashrrev_i32_e32 v25, 31, v24
	v_lshlrev_b64 v[18:19], 12, v[18:19]
	v_ashrrev_i32_e32 v27, 31, v26
	v_ashrrev_i32_e32 v29, 31, v28
	v_ashrrev_i32_e32 v31, 31, v30
	v_ashrrev_i32_e32 v33, 31, v32
	v_lshlrev_b64 v[20:21], 12, v[20:21]
	v_lshlrev_b64 v[22:23], 12, v[22:23]
	v_lshlrev_b64 v[24:25], 12, v[24:25]
	v_lshl_add_u64 v[18:19], v[6:7], 0, v[18:19]
	v_lshlrev_b64 v[26:27], 12, v[26:27]
	v_lshlrev_b64 v[28:29], 12, v[28:29]
	v_lshlrev_b64 v[30:31], 12, v[30:31]
	v_lshlrev_b64 v[32:33], 12, v[32:33]
	v_lshl_add_u64 v[20:21], v[6:7], 0, v[20:21]
	v_lshl_add_u64 v[22:23], v[6:7], 0, v[22:23]
	v_lshl_add_u64 v[24:25], v[6:7], 0, v[24:25]
	v_lshl_add_u64 v[26:27], v[6:7], 0, v[26:27]
	v_lshl_add_u64 v[28:29], v[6:7], 0, v[28:29]
	v_lshl_add_u64 v[30:31], v[6:7], 0, v[30:31]
	v_lshl_add_u64 v[32:33], v[6:7], 0, v[32:33]
	global_load_dword v116, v[18:19], off nt
	s_nop 0
	global_load_dword v117, v[20:21], off nt
	s_nop 0
	global_load_dword v118, v[22:23], off nt
	global_load_dword v119, v[24:25], off nt
	s_nop 0
	global_load_dword v120, v[26:27], off nt
	global_load_dword v121, v[28:29], off nt
	global_load_dword v122, v[30:31], off nt
	global_load_dword v123, v[32:33], off nt
	s_add_i32 s1, s1, 16
	v_add_u32_e32 v18, s1, v16
	v_add_u32_e32 v20, 2, v18
	v_add_u32_e32 v22, 4, v18
	v_add_u32_e32 v24, 6, v18
	v_ashrrev_i32_e32 v19, 31, v18
	v_add_u32_e32 v26, 8, v18
	v_add_u32_e32 v28, 10, v18
	v_add_u32_e32 v30, 12, v18
	v_add_u32_e32 v32, 14, v18
	v_ashrrev_i32_e32 v21, 31, v20
	v_ashrrev_i32_e32 v23, 31, v22
	v_ashrrev_i32_e32 v25, 31, v24
	v_lshlrev_b64 v[18:19], 12, v[18:19]
	v_ashrrev_i32_e32 v27, 31, v26
	v_ashrrev_i32_e32 v29, 31, v28
	v_ashrrev_i32_e32 v31, 31, v30
	v_ashrrev_i32_e32 v33, 31, v32
	v_lshlrev_b64 v[20:21], 12, v[20:21]
	v_lshlrev_b64 v[22:23], 12, v[22:23]
	v_lshlrev_b64 v[24:25], 12, v[24:25]
	v_lshl_add_u64 v[18:19], v[6:7], 0, v[18:19]
	v_lshlrev_b64 v[26:27], 12, v[26:27]
	v_lshlrev_b64 v[28:29], 12, v[28:29]
	v_lshlrev_b64 v[30:31], 12, v[30:31]
	v_lshlrev_b64 v[32:33], 12, v[32:33]
	v_lshl_add_u64 v[20:21], v[6:7], 0, v[20:21]
	v_lshl_add_u64 v[22:23], v[6:7], 0, v[22:23]
	v_lshl_add_u64 v[24:25], v[6:7], 0, v[24:25]
	v_lshl_add_u64 v[26:27], v[6:7], 0, v[26:27]
	v_lshl_add_u64 v[28:29], v[6:7], 0, v[28:29]
	v_lshl_add_u64 v[30:31], v[6:7], 0, v[30:31]
	v_lshl_add_u64 v[32:33], v[6:7], 0, v[32:33]
	global_load_dword v124, v[18:19], off nt
	s_nop 0
	global_load_dword v125, v[20:21], off nt
	s_nop 0
	global_load_dword v126, v[22:23], off nt
	global_load_dword v127, v[24:25], off nt
	s_nop 0
	global_load_dword v128, v[26:27], off nt
	global_load_dword v129, v[28:29], off nt
	global_load_dword v130, v[30:31], off nt
	global_load_dword v131, v[32:33], off nt
	v_add_u32_e32 v132, 0x400, v17
	v_add_u32_e32 v133, 0x840, v17
	v_add_u32_e32 v134, 0xc40, v17
	v_add_u32_e32 v135, 0x1080, v17
	v_add_u32_e32 v136, 0x1480, v17
	v_add_u32_e32 v137, 0x18c0, v17
	v_add_u32_e32 v138, 0x1cc0, v17
	s_waitcnt vmcnt(30)
	ds_write2_b32 v17, v100, v101 offset1:66
	s_waitcnt vmcnt(28)
	ds_write2_b32 v17, v102, v103 offset0:132 offset1:198
	s_waitcnt vmcnt(26)
	ds_write2_b32 v132, v104, v105 offset0:8 offset1:74
	s_waitcnt vmcnt(24)
	ds_write2_b32 v132, v106, v107 offset0:140 offset1:206
	s_waitcnt vmcnt(22)
	ds_write2_b32 v133, v108, v109 offset1:66
	s_waitcnt vmcnt(20)
	ds_write2_b32 v133, v110, v111 offset0:132 offset1:198
	s_waitcnt vmcnt(18)
	ds_write2_b32 v134, v112, v113 offset0:8 offset1:74
	s_waitcnt vmcnt(16)
	ds_write2_b32 v134, v114, v115 offset0:140 offset1:206
	s_waitcnt vmcnt(14)
	ds_write2_b32 v135, v116, v117 offset1:66
	s_waitcnt vmcnt(12)
	ds_write2_b32 v135, v118, v119 offset0:132 offset1:198
	s_waitcnt vmcnt(10)
	ds_write2_b32 v136, v120, v121 offset0:8 offset1:74
	s_waitcnt vmcnt(8)
	ds_write2_b32 v136, v122, v123 offset0:140 offset1:206
	s_waitcnt vmcnt(6)
	ds_write2_b32 v137, v124, v125 offset1:66
	s_waitcnt vmcnt(4)
	ds_write2_b32 v137, v126, v127 offset0:132 offset1:198
	s_waitcnt vmcnt(2)
	ds_write2_b32 v138, v128, v129 offset0:8 offset1:74
	s_waitcnt vmcnt(0)
	ds_write2_b32 v138, v130, v131 offset0:140 offset1:206
	s_waitcnt lgkmcnt(0)
	ds_read2_b32 v[6:7], v9 offset0:33 offset1:41
	ds_read2_b32 v[20:21], v9 offset1:8
	ds_read2_b32 v[22:23], v9 offset0:66 offset1:74
	ds_read2_b32 v[24:25], v9 offset0:99 offset1:107
	ds_read2_b32 v[26:27], v9 offset0:132 offset1:140
	ds_read2_b32 v[28:29], v9 offset0:165 offset1:173
	ds_read2_b32 v[30:31], v9 offset0:198 offset1:206
	ds_read2_b32 v[32:33], v9 offset0:231 offset1:239
	s_waitcnt lgkmcnt(6)
	v_cvt_pk_bf16_f32 v16, v20, v6
	v_or_b32_e32 v6, s0, v8
	v_lshlrev_b32_e32 v6, 2, v6
	v_bitop3_b32 v20, s0, v14, v8 bitop3:0xc8
	v_and_or_b32 v6, v6, 16, v20
	s_ashr_i32 s7, s6, 31
	v_mul_u32_u24_e32 v36, 0x1600, v6
	v_lshl_add_u64 v[34:35], s[6:7], 1, v[4:5]
	v_ashrrev_i32_e32 v37, 31, v36
	v_or_b32_e32 v6, s0, v10
	s_waitcnt lgkmcnt(4)
	v_cvt_pk_bf16_f32 v17, v22, v24
	s_waitcnt lgkmcnt(2)
	v_cvt_pk_bf16_f32 v18, v26, v28
	s_waitcnt lgkmcnt(0)
	v_cvt_pk_bf16_f32 v19, v30, v32
	v_lshl_add_u64 v[36:37], v[34:35], 0, v[36:37]
	v_lshlrev_b32_e32 v6, 2, v6
	global_store_dwordx4 v[36:37], v[16:19], off sc1
	v_and_b32_e32 v6, 16, v6
	s_add_i32 s8, s8, s9
	v_cvt_pk_bf16_f32 v16, v21, v7
	v_bitop3_b32 v7, s0, v15, v10 bitop3:0xc8
	v_or3_b32 v6, v7, v6, 4
	v_cvt_pk_bf16_f32 v17, v23, v25
	v_cvt_pk_bf16_f32 v18, v27, v29
	v_cvt_pk_bf16_f32 v19, v31, v33
	v_mad_i64_i32 v[6:7], s[6:7], v6, s10, v[34:35]
	ds_read2_b32 v[20:21], v9 offset0:16 offset1:24
	ds_read2_b32 v[22:23], v9 offset0:49 offset1:57
	ds_read2_b32 v[24:25], v9 offset0:82 offset1:90
	ds_read2_b32 v[26:27], v9 offset0:115 offset1:123
	ds_read2_b32 v[28:29], v9 offset0:148 offset1:156
	ds_read2_b32 v[30:31], v9 offset0:181 offset1:189
	ds_read2_b32 v[32:33], v9 offset0:214 offset1:222
	ds_read2_b32 v[36:37], v9 offset0:247 offset1:255
	global_store_dwordx4 v[6:7], v[16:19], off sc1
	v_or_b32_e32 v6, s0, v11
	v_lshlrev_b32_e32 v6, 2, v6
	v_and_b32_e32 v6, 16, v6
	v_bitop3_b32 v7, s0, v15, v11 bitop3:0xc8
	v_or3_b32 v6, v7, v6, 8
	s_waitcnt lgkmcnt(6)
	v_cvt_pk_bf16_f32 v16, v20, v22
	s_waitcnt lgkmcnt(4)
	v_cvt_pk_bf16_f32 v17, v24, v26
	s_waitcnt lgkmcnt(2)
	v_cvt_pk_bf16_f32 v18, v28, v30
	s_waitcnt lgkmcnt(0)
	v_cvt_pk_bf16_f32 v19, v32, v36
	v_mad_i64_i32 v[6:7], s[6:7], v6, s10, v[34:35]
	global_store_dwordx4 v[6:7], v[16:19], off sc1
	v_or_b32_e32 v6, s0, v12
	v_lshlrev_b32_e32 v6, 2, v6
	v_and_b32_e32 v6, 16, v6
	v_bitop3_b32 v7, s0, v15, v12 bitop3:0xc8
	v_or3_b32 v6, v7, v6, 12
	v_cvt_pk_bf16_f32 v16, v21, v23
	v_cvt_pk_bf16_f32 v17, v25, v27
	v_cvt_pk_bf16_f32 v18, v29, v31
	v_cvt_pk_bf16_f32 v19, v33, v37
	v_mad_i64_i32 v[6:7], s[0:1], v6, s10, v[34:35]
	global_store_dwordx4 v[6:7], v[16:19], off sc1
	s_waitcnt lgkmcnt(0)
	s_cmpk_lt_i32 s8, 0x580
	s_cbranch_scc1 .LBB0_180

.Ld1a_273:
	v_lshl_add_u64 v[70:71], v[42:43], 0, s[0:1]
	v_lshl_add_u64 v[72:73], v[40:41], 0, s[0:1]
	v_lshl_add_u64 v[74:75], v[38:39], 0, s[0:1]
	v_lshl_add_u64 v[76:77], v[36:37], 0, s[0:1]
	v_lshl_add_u64 v[78:79], v[34:35], 0, s[0:1]
	v_lshl_add_u64 v[80:81], v[32:33], 0, s[0:1]
	v_lshl_add_u64 v[82:83], v[30:31], 0, s[0:1]
	v_lshl_add_u64 v[84:85], v[28:29], 0, s[0:1]
	global_load_dword v100, v[70:71], off nt
	s_nop 0
	global_load_dword v101, v[72:73], off nt
	global_load_dword v102, v[74:75], off nt
	s_nop 0
	global_load_dword v103, v[76:77], off nt
	global_load_dword v104, v[78:79], off nt
	global_load_dword v105, v[80:81], off nt
	global_load_dword v106, v[82:83], off nt
	s_nop 0
	global_load_dword v107, v[84:85], off nt
	s_add_u32 s0, s0, 0x8000
	s_addc_u32 s1, s1, 0
	v_lshl_add_u64 v[70:71], v[42:43], 0, s[0:1]
	v_lshl_add_u64 v[72:73], v[40:41], 0, s[0:1]
	v_lshl_add_u64 v[74:75], v[38:39], 0, s[0:1]
	v_lshl_add_u64 v[76:77], v[36:37], 0, s[0:1]
	v_lshl_add_u64 v[78:79], v[34:35], 0, s[0:1]
	v_lshl_add_u64 v[80:81], v[32:33], 0, s[0:1]
	v_lshl_add_u64 v[82:83], v[30:31], 0, s[0:1]
	v_lshl_add_u64 v[84:85], v[28:29], 0, s[0:1]
	global_load_dword v108, v[70:71], off nt
	s_nop 0
	global_load_dword v109, v[72:73], off nt
	global_load_dword v110, v[74:75], off nt
	s_nop 0
	global_load_dword v111, v[76:77], off nt
	global_load_dword v112, v[78:79], off nt
	global_load_dword v113, v[80:81], off nt
	global_load_dword v114, v[82:83], off nt
	s_nop 0
	global_load_dword v115, v[84:85], off nt
	s_add_u32 s0, s0, 0x8000
	s_addc_u32 s1, s1, 0
	v_lshl_add_u64 v[70:71], v[42:43], 0, s[0:1]
	v_lshl_add_u64 v[72:73], v[40:41], 0, s[0:1]
	v_lshl_add_u64 v[74:75], v[38:39], 0, s[0:1]
	v_lshl_add_u64 v[76:77], v[36:37], 0, s[0:1]
	v_lshl_add_u64 v[78:79], v[34:35], 0, s[0:1]
	v_lshl_add_u64 v[80:81], v[32:33], 0, s[0:1]
	v_lshl_add_u64 v[82:83], v[30:31], 0, s[0:1]
	v_lshl_add_u64 v[84:85], v[28:29], 0, s[0:1]
	global_load_dword v116, v[70:71], off nt
	s_nop 0
	global_load_dword v117, v[72:73], off nt
	global_load_dword v118, v[74:75], off nt
	s_nop 0
	global_load_dword v119, v[76:77], off nt
	global_load_dword v120, v[78:79], off nt
	global_load_dword v121, v[80:81], off nt
	global_load_dword v122, v[82:83], off nt
	s_nop 0
	global_load_dword v123, v[84:85], off nt
	s_add_u32 s0, s0, 0x8000
	s_addc_u32 s1, s1, 0
	v_lshl_add_u64 v[70:71], v[42:43], 0, s[0:1]
	v_lshl_add_u64 v[72:73], v[40:41], 0, s[0:1]
	v_lshl_add_u64 v[74:75], v[38:39], 0, s[0:1]
	v_lshl_add_u64 v[76:77], v[36:37], 0, s[0:1]
	v_lshl_add_u64 v[78:79], v[34:35], 0, s[0:1]
	v_lshl_add_u64 v[80:81], v[32:33], 0, s[0:1]
	v_lshl_add_u64 v[82:83], v[30:31], 0, s[0:1]
	v_lshl_add_u64 v[84:85], v[28:29], 0, s[0:1]
	global_load_dword v124, v[70:71], off nt
	s_nop 0
	global_load_dword v125, v[72:73], off nt
	global_load_dword v126, v[74:75], off nt
	s_nop 0
	global_load_dword v127, v[76:77], off nt
	global_load_dword v128, v[78:79], off nt
	global_load_dword v129, v[80:81], off nt
	global_load_dword v130, v[82:83], off nt
	s_nop 0
	global_load_dword v131, v[84:85], off nt
	v_add_u32_e32 v132, 0x400, v2
	v_add_u32_e32 v133, 0x840, v2
	v_add_u32_e32 v134, 0xc40, v2
	v_add_u32_e32 v135, 0x1080, v2
	v_add_u32_e32 v136, 0x1480, v2
	v_add_u32_e32 v137, 0x18c0, v2
	v_add_u32_e32 v138, 0x1cc0, v2
	s_waitcnt vmcnt(30)
	ds_write2_b32 v2, v100, v101 offset1:66
	s_waitcnt vmcnt(28)
	ds_write2_b32 v2, v102, v103 offset0:132 offset1:198
	s_waitcnt vmcnt(26)
	ds_write2_b32 v132, v104, v105 offset0:8 offset1:74
	s_waitcnt vmcnt(24)
	ds_write2_b32 v132, v106, v107 offset0:140 offset1:206
	s_waitcnt vmcnt(22)
	ds_write2_b32 v133, v108, v109 offset1:66
	s_waitcnt vmcnt(20)
	ds_write2_b32 v133, v110, v111 offset0:132 offset1:198
	s_waitcnt vmcnt(18)
	ds_write2_b32 v134, v112, v113 offset0:8 offset1:74
	s_waitcnt vmcnt(16)
	ds_write2_b32 v134, v114, v115 offset0:140 offset1:206
	s_waitcnt vmcnt(14)
	ds_write2_b32 v135, v116, v117 offset1:66
	s_waitcnt vmcnt(12)
	ds_write2_b32 v135, v118, v119 offset0:132 offset1:198
	s_waitcnt vmcnt(10)
	ds_write2_b32 v136, v120, v121 offset0:8 offset1:74
	s_waitcnt vmcnt(8)
	ds_write2_b32 v136, v122, v123 offset0:140 offset1:206
	s_waitcnt vmcnt(6)
	ds_write2_b32 v137, v124, v125 offset1:66
	s_waitcnt vmcnt(4)
	ds_write2_b32 v137, v126, v127 offset0:132 offset1:198
	s_waitcnt vmcnt(2)
	ds_write2_b32 v138, v128, v129 offset0:8 offset1:74
	s_waitcnt vmcnt(0)
	ds_write2_b32 v138, v130, v131 offset0:140 offset1:206
	s_add_i32 s0, s61, 0xffffe780
	s_lshr_b32 s0, s0, 7
	s_lshl_b32 s1, s61, 5
	s_and_b32 s4, s1, 0x1e0
	s_mul_hi_u32 s1, s0, 0x180000
	s_mul_i32 s0, s0, 0x180000
	s_waitcnt lgkmcnt(0)
	s_add_u32 s0, s18, s0
	s_addc_u32 s1, s19, s1
	s_lshl_b32 s8, s61, 3
	ds_read2_b32 v[32:33], v44 offset0:33 offset1:41
	ds_read2_b32 v[34:35], v44 offset1:8
	ds_read2_b32 v[36:37], v44 offset0:66 offset1:74
	ds_read2_b32 v[38:39], v44 offset0:99 offset1:107
	ds_read2_b32 v[40:41], v44 offset0:132 offset1:140
	ds_read2_b32 v[42:43], v44 offset0:165 offset1:173
	ds_read2_b32 v[70:71], v44 offset0:198 offset1:206
	ds_read2_b32 v[72:73], v44 offset0:231 offset1:239
	s_and_b32 s8, s8, 0x380
	s_add_u32 s0, s0, s8
	s_addc_u32 s1, s1, 0
	v_mov_b32_e32 v27, v3
	v_or_b32_e32 v2, s4, v19
	v_lshl_add_u64 v[74:75], s[0:1], 0, v[26:27]
	v_mul_u32_u24_e32 v2, 0xc00, v2
	s_waitcnt lgkmcnt(6)
	v_cvt_pk_bf16_f32 v28, v34, v32
	s_waitcnt lgkmcnt(4)
	v_cvt_pk_bf16_f32 v29, v36, v38
	s_waitcnt lgkmcnt(2)
	v_cvt_pk_bf16_f32 v30, v40, v42
	s_waitcnt lgkmcnt(0)
	v_cvt_pk_bf16_f32 v31, v70, v72
	v_lshl_add_u64 v[76:77], v[74:75], 0, v[2:3]
	global_store_dwordx4 v[76:77], v[28:31], off sc1
	v_or_b32_e32 v2, s4, v45
	v_mul_u32_u24_e32 v2, 0xc00, v2
	v_cvt_pk_bf16_f32 v28, v35, v33
	v_cvt_pk_bf16_f32 v29, v37, v39
	v_cvt_pk_bf16_f32 v30, v41, v43
	v_cvt_pk_bf16_f32 v31, v71, v73
	ds_read2_b32 v[34:35], v44 offset0:16 offset1:24
	ds_read2_b32 v[36:37], v44 offset0:49 offset1:57
	ds_read2_b32 v[38:39], v44 offset0:82 offset1:90
	ds_read2_b32 v[40:41], v44 offset0:115 offset1:123
	ds_read2_b32 v[42:43], v44 offset0:148 offset1:156
	ds_read2_b32 v[70:71], v44 offset0:181 offset1:189
	ds_read2_b32 v[72:73], v44 offset0:214 offset1:222
	ds_read2_b32 v[76:77], v44 offset0:247 offset1:255
	v_lshl_add_u64 v[32:33], v[74:75], 0, v[2:3]
	v_or_b32_e32 v2, s4, v46
	v_mul_u32_u24_e32 v2, 0xc00, v2
	global_store_dwordx4 v[32:33], v[28:31], off sc1
	v_lshl_add_u64 v[32:33], v[74:75], 0, v[2:3]
	v_or_b32_e32 v2, s4, v47
	s_waitcnt lgkmcnt(6)
	v_cvt_pk_bf16_f32 v28, v34, v36
	s_waitcnt lgkmcnt(4)
	v_cvt_pk_bf16_f32 v29, v38, v40
	s_waitcnt lgkmcnt(2)
	v_cvt_pk_bf16_f32 v30, v42, v70
	s_waitcnt lgkmcnt(0)
	v_cvt_pk_bf16_f32 v31, v72, v76
	v_mul_u32_u24_e32 v2, 0xc00, v2
	global_store_dwordx4 v[32:33], v[28:31], off sc1
	v_lshl_add_u64 v[32:33], v[74:75], 0, v[2:3]
	s_mov_b64 s[0:1], 0
	v_cvt_pk_bf16_f32 v28, v35, v37
	v_cvt_pk_bf16_f32 v29, v39, v41
	v_cvt_pk_bf16_f32 v30, v43, v71
	v_cvt_pk_bf16_f32 v31, v73, v77
	global_store_dwordx4 v[32:33], v[28:31], off sc1
	s_waitcnt lgkmcnt(0)

.Ld1a_277:
	v_lshl_add_u64 v[70:71], v[42:43], 0, s[0:1]
	v_lshl_add_u64 v[72:73], v[40:41], 0, s[0:1]
	v_lshl_add_u64 v[74:75], v[38:39], 0, s[0:1]
	v_lshl_add_u64 v[76:77], v[36:37], 0, s[0:1]
	v_lshl_add_u64 v[78:79], v[34:35], 0, s[0:1]
	v_lshl_add_u64 v[80:81], v[32:33], 0, s[0:1]
	v_lshl_add_u64 v[82:83], v[30:31], 0, s[0:1]
	v_lshl_add_u64 v[84:85], v[28:29], 0, s[0:1]
	global_load_dword v100, v[70:71], off nt
	s_nop 0
	global_load_dword v101, v[72:73], off nt
	global_load_dword v102, v[74:75], off nt
	s_nop 0
	global_load_dword v103, v[76:77], off nt
	global_load_dword v104, v[78:79], off nt
	global_load_dword v105, v[80:81], off nt
	global_load_dword v106, v[82:83], off nt
	s_nop 0
	global_load_dword v107, v[84:85], off nt
	s_add_u32 s0, s0, 0x10000
	s_addc_u32 s1, s1, 0
	v_lshl_add_u64 v[70:71], v[42:43], 0, s[0:1]
	v_lshl_add_u64 v[72:73], v[40:41], 0, s[0:1]
	v_lshl_add_u64 v[74:75], v[38:39], 0, s[0:1]
	v_lshl_add_u64 v[76:77], v[36:37], 0, s[0:1]
	v_lshl_add_u64 v[78:79], v[34:35], 0, s[0:1]
	v_lshl_add_u64 v[80:81], v[32:33], 0, s[0:1]
	v_lshl_add_u64 v[82:83], v[30:31], 0, s[0:1]
	v_lshl_add_u64 v[84:85], v[28:29], 0, s[0:1]
	global_load_dword v108, v[70:71], off nt
	s_nop 0
	global_load_dword v109, v[72:73], off nt
	global_load_dword v110, v[74:75], off nt
	s_nop 0
	global_load_dword v111, v[76:77], off nt
	global_load_dword v112, v[78:79], off nt
	global_load_dword v113, v[80:81], off nt
	global_load_dword v114, v[82:83], off nt
	s_nop 0
	global_load_dword v115, v[84:85], off nt
	s_add_u32 s0, s0, 0x10000
	s_addc_u32 s1, s1, 0
	v_lshl_add_u64 v[70:71], v[42:43], 0, s[0:1]
	v_lshl_add_u64 v[72:73], v[40:41], 0, s[0:1]
	v_lshl_add_u64 v[74:75], v[38:39], 0, s[0:1]
	v_lshl_add_u64 v[76:77], v[36:37], 0, s[0:1]
	v_lshl_add_u64 v[78:79], v[34:35], 0, s[0:1]
	v_lshl_add_u64 v[80:81], v[32:33], 0, s[0:1]
	v_lshl_add_u64 v[82:83], v[30:31], 0, s[0:1]
	v_lshl_add_u64 v[84:85], v[28:29], 0, s[0:1]
	global_load_dword v116, v[70:71], off nt
	s_nop 0
	global_load_dword v117, v[72:73], off nt
	global_load_dword v118, v[74:75], off nt
	s_nop 0
	global_load_dword v119, v[76:77], off nt
	global_load_dword v120, v[78:79], off nt
	global_load_dword v121, v[80:81], off nt
	global_load_dword v122, v[82:83], off nt
	s_nop 0
	global_load_dword v123, v[84:85], off nt
	s_add_u32 s0, s0, 0x10000
	s_addc_u32 s1, s1, 0
	v_lshl_add_u64 v[70:71], v[42:43], 0, s[0:1]
	v_lshl_add_u64 v[72:73], v[40:41], 0, s[0:1]
	v_lshl_add_u64 v[74:75], v[38:39], 0, s[0:1]
	v_lshl_add_u64 v[76:77], v[36:37], 0, s[0:1]
	v_lshl_add_u64 v[78:79], v[34:35], 0, s[0:1]
	v_lshl_add_u64 v[80:81], v[32:33], 0, s[0:1]
	v_lshl_add_u64 v[82:83], v[30:31], 0, s[0:1]
	v_lshl_add_u64 v[84:85], v[28:29], 0, s[0:1]
	global_load_dword v124, v[70:71], off nt
	s_nop 0
	global_load_dword v125, v[72:73], off nt
	global_load_dword v126, v[74:75], off nt
	s_nop 0
	global_load_dword v127, v[76:77], off nt
	global_load_dword v128, v[78:79], off nt
	global_load_dword v129, v[80:81], off nt
	global_load_dword v130, v[82:83], off nt
	s_nop 0
	global_load_dword v131, v[84:85], off nt
	v_add_u32_e32 v132, 0x400, v2
	v_add_u32_e32 v133, 0x840, v2
	v_add_u32_e32 v134, 0xc40, v2
	v_add_u32_e32 v135, 0x1080, v2
	v_add_u32_e32 v136, 0x1480, v2
	v_add_u32_e32 v137, 0x18c0, v2
	v_add_u32_e32 v138, 0x1cc0, v2
	s_waitcnt vmcnt(30)
	ds_write2_b32 v2, v100, v101 offset1:66
	s_waitcnt vmcnt(28)
	ds_write2_b32 v2, v102, v103 offset0:132 offset1:198
	s_waitcnt vmcnt(26)
	ds_write2_b32 v132, v104, v105 offset0:8 offset1:74
	s_waitcnt vmcnt(24)
	ds_write2_b32 v132, v106, v107 offset0:140 offset1:206
	s_waitcnt vmcnt(22)
	ds_write2_b32 v133, v108, v109 offset1:66
	s_waitcnt vmcnt(20)
	ds_write2_b32 v133, v110, v111 offset0:132 offset1:198
	s_waitcnt vmcnt(18)
	ds_write2_b32 v134, v112, v113 offset0:8 offset1:74
	s_waitcnt vmcnt(16)
	ds_write2_b32 v134, v114, v115 offset0:140 offset1:206
	s_waitcnt vmcnt(14)
	ds_write2_b32 v135, v116, v117 offset1:66
	s_waitcnt vmcnt(12)
	ds_write2_b32 v135, v118, v119 offset0:132 offset1:198
	s_waitcnt vmcnt(10)
	ds_write2_b32 v136, v120, v121 offset0:8 offset1:74
	s_waitcnt vmcnt(8)
	ds_write2_b32 v136, v122, v123 offset0:140 offset1:206
	s_waitcnt vmcnt(6)
	ds_write2_b32 v137, v124, v125 offset1:66
	s_waitcnt vmcnt(4)
	ds_write2_b32 v137, v126, v127 offset0:132 offset1:198
	s_waitcnt vmcnt(2)
	ds_write2_b32 v138, v128, v129 offset0:8 offset1:74
	s_waitcnt vmcnt(0)
	ds_write2_b32 v138, v130, v131 offset0:140 offset1:206
	s_waitcnt lgkmcnt(0)
	s_lshl_b32 s0, s61, 1
	ds_read2_b32 v[32:33], v44 offset0:33 offset1:41
	ds_read2_b32 v[34:35], v44 offset1:8
	ds_read2_b32 v[36:37], v44 offset0:66 offset1:74
	ds_read2_b32 v[38:39], v44 offset0:99 offset1:107
	ds_read2_b32 v[40:41], v44 offset0:132 offset1:140
	ds_read2_b32 v[42:43], v44 offset0:165 offset1:173
	ds_read2_b32 v[70:71], v44 offset0:198 offset1:206
	ds_read2_b32 v[72:73], v44 offset0:231 offset1:239
	s_add_i32 s0, s0, 0x7fffd300
	s_and_b32 s0, s0, 0x7fffffc0
	v_lshl_or_b32 v27, s61, 5, v19
	s_lshl_b32 s4, s0, 1
	v_and_or_b32 v2, v27, s45, v48
	v_lshl_add_u64 v[74:75], v[4:5], 0, s[4:5]
	v_lshlrev_b32_e32 v2, 11, v2
	s_waitcnt lgkmcnt(6)
	v_cvt_pk_bf16_f32 v28, v34, v32
	s_waitcnt lgkmcnt(4)
	v_cvt_pk_bf16_f32 v29, v36, v38
	s_waitcnt lgkmcnt(2)
	v_cvt_pk_bf16_f32 v30, v40, v42
	s_waitcnt lgkmcnt(0)
	v_cvt_pk_bf16_f32 v31, v70, v72
	v_lshl_add_u64 v[76:77], v[74:75], 0, v[2:3]
	global_store_dwordx4 v[76:77], v[28:31], off sc1
	v_add_co_u32_e32 v32, vcc, s46, v76
	s_nop 0
	v_cvt_pk_bf16_f32 v28, v35, v33
	v_cvt_pk_bf16_f32 v29, v37, v39
	v_cvt_pk_bf16_f32 v30, v41, v43
	v_cvt_pk_bf16_f32 v31, v71, v73
	ds_read2_b32 v[34:35], v44 offset0:49 offset1:57
	ds_read2_b32 v[36:37], v44 offset0:16 offset1:24
	ds_read2_b32 v[38:39], v44 offset0:82 offset1:90
	ds_read2_b32 v[40:41], v44 offset0:115 offset1:123
	ds_read2_b32 v[42:43], v44 offset0:148 offset1:156
	ds_read2_b32 v[70:71], v44 offset0:181 offset1:189
	ds_read2_b32 v[72:73], v44 offset0:214 offset1:222
	ds_read2_b32 v[78:79], v44 offset0:247 offset1:255
	v_addc_co_u32_e32 v33, vcc, 0, v77, vcc
	global_store_dwordx4 v[32:33], v[28:31], off sc1
	v_add_co_u32_e32 v32, vcc, s47, v76
	v_lshlrev_b32_e32 v2, 11, v27
	s_waitcnt lgkmcnt(6)
	v_cvt_pk_bf16_f32 v28, v36, v34
	s_waitcnt lgkmcnt(4)
	v_cvt_pk_bf16_f32 v29, v38, v40
	s_waitcnt lgkmcnt(2)
	v_cvt_pk_bf16_f32 v30, v42, v70
	s_waitcnt lgkmcnt(0)
	v_cvt_pk_bf16_f32 v31, v72, v78
	v_addc_co_u32_e32 v33, vcc, 0, v77, vcc
	v_and_or_b32 v2, v2, s48, v49
	global_store_dwordx4 v[32:33], v[28:31], off sc1
	v_lshl_add_u64 v[32:33], v[74:75], 0, v[2:3]
	s_nop 0
	v_cvt_pk_bf16_f32 v28, v37, v35
	v_cvt_pk_bf16_f32 v29, v39, v41
	v_cvt_pk_bf16_f32 v30, v43, v71
	v_cvt_pk_bf16_f32 v31, v73, v79
	global_store_dwordx4 v[32:33], v[28:31], off sc1
	s_waitcnt lgkmcnt(0)

.Ld1a_289:
	s_and_b32 s0, 0xffff, s63
	s_lshl_b32 s4, s0, 1
	v_lshl_add_u64 v[28:29], v[6:7], 0, s[4:5]
	s_waitcnt lgkmcnt(3)
	v_cvt_pk_bf16_f32 v30, v30, v31
	s_waitcnt lgkmcnt(2)
	v_cvt_pk_bf16_f32 v31, v32, v33
	s_waitcnt lgkmcnt(1)
	v_cvt_pk_bf16_f32 v32, v34, v35
	v_lshlrev_b64 v[34:35], 11, v[2:3]
	s_waitcnt lgkmcnt(0)
	v_cvt_pk_bf16_f32 v33, v36, v37
	v_lshl_add_u64 v[34:35], v[28:29], 0, v[34:35]
	global_store_dwordx4 v[34:35], v[30:33], off sc1
	ds_read2_b32 v[30:31], v44 offset0:8 offset1:41
	ds_read2_b32 v[32:33], v44 offset0:74 offset1:107
	ds_read2_b32 v[34:35], v44 offset0:140 offset1:173
	ds_read2_b32 v[36:37], v44 offset0:206 offset1:239
	v_cndmask_b32_e64 v2, 0, 1, s[8:9]
	v_cmp_ne_u32_e64 s[0:1], 1, v2
	s_andn2_b64 vcc, exec, s[8:9]
	v_or_b32_e32 v2, s11, v45
	s_cbranch_vccnz .Ld1a_295
	s_cmp_lt_u32 s62, 64
	s_mov_b64 s[8:9], -1
	s_cbranch_scc1 .Ld1a_292
	v_add_u32_e32 v27, 0xfffff800, v2
	s_lshl_b32 s4, s11, 1
	s_and_b32 s4, s4, 0x300
	v_lshrrev_b32_e32 v27, 2, v27
	v_and_b32_e32 v38, 0x63, v2
	v_and_b32_e32 v27, 0x3fffff80, v27
	v_or3_b32 v38, s4, v38, v51
	v_add_u32_e32 v27, v38, v27
	s_mov_b64 s[8:9], 0

.Ld1a_295:
	s_waitcnt lgkmcnt(3)
	v_cvt_pk_bf16_f32 v38, v30, v31
	s_waitcnt lgkmcnt(2)
	v_cvt_pk_bf16_f32 v39, v32, v33
	s_waitcnt lgkmcnt(1)
	v_cvt_pk_bf16_f32 v40, v34, v35
	s_waitcnt lgkmcnt(0)
	v_cvt_pk_bf16_f32 v41, v36, v37
	ds_read2_b32 v[30:31], v44 offset0:16 offset1:49
	ds_read2_b32 v[32:33], v44 offset0:82 offset1:115
	ds_read2_b32 v[34:35], v44 offset0:148 offset1:181
	ds_read2_b32 v[36:37], v44 offset0:214 offset1:247
	v_lshlrev_b64 v[42:43], 11, v[2:3]
	v_lshl_add_u64 v[42:43], v[28:29], 0, v[42:43]
	s_and_b64 vcc, exec, s[0:1]
	v_or_b32_e32 v2, s11, v46
	global_store_dwordx4 v[42:43], v[38:41], off sc1
	s_cbranch_vccnz .Ld1a_301
	s_cmp_lt_u32 s62, 64
	s_mov_b64 s[8:9], -1
	s_cbranch_scc1 .Ld1a_298
	v_add_u32_e32 v27, 0xfffff800, v2
	s_lshl_b32 s4, s11, 1
	s_and_b32 s4, s4, 0x300
	v_lshrrev_b32_e32 v27, 2, v27
	v_and_b32_e32 v38, 0x63, v2
	v_and_b32_e32 v27, 0x3fffff80, v27
	v_or3_b32 v38, s4, v38, v53
	v_add_u32_e32 v27, v38, v27
	s_mov_b64 s[8:9], 0

.Ld1a_301:
	s_waitcnt lgkmcnt(3)
	v_cvt_pk_bf16_f32 v38, v30, v31
	s_waitcnt lgkmcnt(2)
	v_cvt_pk_bf16_f32 v39, v32, v33
	s_waitcnt lgkmcnt(1)
	v_cvt_pk_bf16_f32 v40, v34, v35
	s_waitcnt lgkmcnt(0)
	v_cvt_pk_bf16_f32 v41, v36, v37
	ds_read2_b32 v[30:31], v44 offset0:24 offset1:57
	ds_read2_b32 v[32:33], v44 offset0:90 offset1:123
	ds_read2_b32 v[34:35], v44 offset0:156 offset1:189
	ds_read2_b32 v[36:37], v44 offset0:222 offset1:255
	v_lshlrev_b64 v[42:43], 11, v[2:3]
	v_lshl_add_u64 v[42:43], v[28:29], 0, v[42:43]
	s_and_b64 vcc, exec, s[0:1]
	v_or_b32_e32 v2, s11, v47
	global_store_dwordx4 v[42:43], v[38:41], off sc1
	s_cbranch_vccnz .Ld1a_307
	s_cmp_lt_u32 s62, 64
	s_mov_b64 s[0:1], -1
	s_cbranch_scc1 .Ld1a_304
	v_add_u32_e32 v27, 0xfffff800, v2
	s_lshl_b32 s0, s11, 1
	s_and_b32 s0, s0, 0x300
	v_lshrrev_b32_e32 v27, 2, v27
	v_and_b32_e32 v38, 0x63, v2
	v_and_b32_e32 v27, 0x3fffff80, v27
	v_or3_b32 v38, v38, s0, v55
	v_add_u32_e32 v27, v38, v27
	s_mov_b64 s[0:1], 0

.Ld1a_307:
	s_waitcnt lgkmcnt(3)
	v_cvt_pk_bf16_f32 v30, v30, v31
	s_waitcnt lgkmcnt(2)
	v_cvt_pk_bf16_f32 v31, v32, v33
	s_waitcnt lgkmcnt(1)
	v_cvt_pk_bf16_f32 v32, v34, v35
	v_lshlrev_b64 v[34:35], 11, v[2:3]
	s_waitcnt lgkmcnt(0)
	v_cvt_pk_bf16_f32 v33, v36, v37
	v_lshl_add_u64 v[28:29], v[28:29], 0, v[34:35]
	global_store_dwordx4 v[28:29], v[30:33], off sc1
	s_waitcnt lgkmcnt(0)

.Ld1a_311:
	v_lshl_add_u64 v[70:71], v[42:43], 0, s[0:1]
	v_lshl_add_u64 v[72:73], v[40:41], 0, s[0:1]
	v_lshl_add_u64 v[74:75], v[38:39], 0, s[0:1]
	v_lshl_add_u64 v[76:77], v[36:37], 0, s[0:1]
	v_lshl_add_u64 v[78:79], v[34:35], 0, s[0:1]
	v_lshl_add_u64 v[80:81], v[32:33], 0, s[0:1]
	v_lshl_add_u64 v[82:83], v[30:31], 0, s[0:1]
	v_lshl_add_u64 v[84:85], v[28:29], 0, s[0:1]
	global_load_dword v100, v[70:71], off nt
	s_nop 0
	global_load_dword v101, v[72:73], off nt
	global_load_dword v102, v[74:75], off nt
	s_nop 0
	global_load_dword v103, v[76:77], off nt
	global_load_dword v104, v[78:79], off nt
	global_load_dword v105, v[80:81], off nt
	global_load_dword v106, v[82:83], off nt
	s_nop 0
	global_load_dword v107, v[84:85], off nt
	s_add_u32 s0, s0, 0x10000
	s_addc_u32 s1, s1, 0
	v_lshl_add_u64 v[70:71], v[42:43], 0, s[0:1]
	v_lshl_add_u64 v[72:73], v[40:41], 0, s[0:1]
	v_lshl_add_u64 v[74:75], v[38:39], 0, s[0:1]
	v_lshl_add_u64 v[76:77], v[36:37], 0, s[0:1]
	v_lshl_add_u64 v[78:79], v[34:35], 0, s[0:1]
	v_lshl_add_u64 v[80:81], v[32:33], 0, s[0:1]
	v_lshl_add_u64 v[82:83], v[30:31], 0, s[0:1]
	v_lshl_add_u64 v[84:85], v[28:29], 0, s[0:1]
	global_load_dword v108, v[70:71], off nt
	s_nop 0
	global_load_dword v109, v[72:73], off nt
	global_load_dword v110, v[74:75], off nt
	s_nop 0
	global_load_dword v111, v[76:77], off nt
	global_load_dword v112, v[78:79], off nt
	global_load_dword v113, v[80:81], off nt
	global_load_dword v114, v[82:83], off nt
	s_nop 0
	global_load_dword v115, v[84:85], off nt
	s_add_u32 s0, s0, 0x10000
	s_addc_u32 s1, s1, 0
	v_lshl_add_u64 v[70:71], v[42:43], 0, s[0:1]
	v_lshl_add_u64 v[72:73], v[40:41], 0, s[0:1]
	v_lshl_add_u64 v[74:75], v[38:39], 0, s[0:1]
	v_lshl_add_u64 v[76:77], v[36:37], 0, s[0:1]
	v_lshl_add_u64 v[78:79], v[34:35], 0, s[0:1]
	v_lshl_add_u64 v[80:81], v[32:33], 0, s[0:1]
	v_lshl_add_u64 v[82:83], v[30:31], 0, s[0:1]
	v_lshl_add_u64 v[84:85], v[28:29], 0, s[0:1]
	global_load_dword v116, v[70:71], off nt
	s_nop 0
	global_load_dword v117, v[72:73], off nt
	global_load_dword v118, v[74:75], off nt
	s_nop 0
	global_load_dword v119, v[76:77], off nt
	global_load_dword v120, v[78:79], off nt
	global_load_dword v121, v[80:81], off nt
	global_load_dword v122, v[82:83], off nt
	s_nop 0
	global_load_dword v123, v[84:85], off nt
	s_add_u32 s0, s0, 0x10000
	s_addc_u32 s1, s1, 0
	v_lshl_add_u64 v[70:71], v[42:43], 0, s[0:1]
	v_lshl_add_u64 v[72:73], v[40:41], 0, s[0:1]
	v_lshl_add_u64 v[74:75], v[38:39], 0, s[0:1]
	v_lshl_add_u64 v[76:77], v[36:37], 0, s[0:1]
	v_lshl_add_u64 v[78:79], v[34:35], 0, s[0:1]
	v_lshl_add_u64 v[80:81], v[32:33], 0, s[0:1]
	v_lshl_add_u64 v[82:83], v[30:31], 0, s[0:1]
	v_lshl_add_u64 v[84:85], v[28:29], 0, s[0:1]
	global_load_dword v124, v[70:71], off nt
	s_nop 0
	global_load_dword v125, v[72:73], off nt
	global_load_dword v126, v[74:75], off nt
	s_nop 0
	global_load_dword v127, v[76:77], off nt
	global_load_dword v128, v[78:79], off nt
	global_load_dword v129, v[80:81], off nt
	global_load_dword v130, v[82:83], off nt
	s_nop 0
	global_load_dword v131, v[84:85], off nt
	v_add_u32_e32 v132, 0x400, v2
	v_add_u32_e32 v133, 0x840, v2
	v_add_u32_e32 v134, 0xc40, v2
	v_add_u32_e32 v135, 0x1080, v2
	v_add_u32_e32 v136, 0x1480, v2
	v_add_u32_e32 v137, 0x18c0, v2
	v_add_u32_e32 v138, 0x1cc0, v2
	s_waitcnt vmcnt(30)
	ds_write2_b32 v2, v100, v101 offset1:66
	s_waitcnt vmcnt(28)
	ds_write2_b32 v2, v102, v103 offset0:132 offset1:198
	s_waitcnt vmcnt(26)
	ds_write2_b32 v132, v104, v105 offset0:8 offset1:74
	s_waitcnt vmcnt(24)
	ds_write2_b32 v132, v106, v107 offset0:140 offset1:206
	s_waitcnt vmcnt(22)
	ds_write2_b32 v133, v108, v109 offset1:66
	s_waitcnt vmcnt(20)
	ds_write2_b32 v133, v110, v111 offset0:132 offset1:198
	s_waitcnt vmcnt(18)
	ds_write2_b32 v134, v112, v113 offset0:8 offset1:74
	s_waitcnt vmcnt(16)
	ds_write2_b32 v134, v114, v115 offset0:140 offset1:206
	s_waitcnt vmcnt(14)
	ds_write2_b32 v135, v116, v117 offset1:66
	s_waitcnt vmcnt(12)
	ds_write2_b32 v135, v118, v119 offset0:132 offset1:198
	s_waitcnt vmcnt(10)
	ds_write2_b32 v136, v120, v121 offset0:8 offset1:74
	s_waitcnt vmcnt(8)
	ds_write2_b32 v136, v122, v123 offset0:140 offset1:206
	s_waitcnt vmcnt(6)
	ds_write2_b32 v137, v124, v125 offset1:66
	s_waitcnt vmcnt(4)
	ds_write2_b32 v137, v126, v127 offset0:132 offset1:198
	s_waitcnt vmcnt(2)
	ds_write2_b32 v138, v128, v129 offset0:8 offset1:74
	s_waitcnt vmcnt(0)
	ds_write2_b32 v138, v130, v131 offset0:140 offset1:206
	s_waitcnt lgkmcnt(0)
	s_lshl_b32 s0, s61, 1
	ds_read2_b32 v[32:33], v44 offset0:33 offset1:41
	ds_read2_b32 v[34:35], v44 offset1:8
	ds_read2_b32 v[36:37], v44 offset0:66 offset1:74
	ds_read2_b32 v[38:39], v44 offset0:99 offset1:107
	ds_read2_b32 v[40:41], v44 offset0:132 offset1:140
	ds_read2_b32 v[42:43], v44 offset0:165 offset1:173
	ds_read2_b32 v[70:71], v44 offset0:198 offset1:206
	ds_read2_b32 v[72:73], v44 offset0:231 offset1:239
	s_add_i32 s0, s0, 0x7fffea00
	s_lshl_b32 s1, s61, 5
	s_and_b32 s0, s0, 0x7fffffc0
	v_bitop3_b32 v27, s1, v65, v19 bitop3:0xc8
	s_lshl_b32 s4, s0, 1
	v_or_b32_e32 v2, v27, v48
	v_lshl_add_u64 v[74:75], v[8:9], 0, s[4:5]
	v_mul_u32_u24_e32 v2, 0x1600, v2
	s_waitcnt lgkmcnt(6)
	v_cvt_pk_bf16_f32 v28, v34, v32
	s_waitcnt lgkmcnt(4)
	v_cvt_pk_bf16_f32 v29, v36, v38
	s_waitcnt lgkmcnt(2)
	v_cvt_pk_bf16_f32 v30, v40, v42
	s_waitcnt lgkmcnt(0)
	v_cvt_pk_bf16_f32 v31, v70, v72
	v_lshl_add_u64 v[76:77], v[74:75], 0, v[2:3]
	global_store_dwordx4 v[76:77], v[28:31], off sc1
	v_add_co_u32_e32 v32, vcc, s56, v76
	s_nop 0
	v_cvt_pk_bf16_f32 v28, v35, v33
	v_cvt_pk_bf16_f32 v29, v37, v39
	v_cvt_pk_bf16_f32 v30, v41, v43
	v_cvt_pk_bf16_f32 v31, v71, v73
	ds_read2_b32 v[34:35], v44 offset0:49 offset1:57
	ds_read2_b32 v[36:37], v44 offset0:16 offset1:24
	ds_read2_b32 v[38:39], v44 offset0:82 offset1:90
	ds_read2_b32 v[40:41], v44 offset0:115 offset1:123
	ds_read2_b32 v[42:43], v44 offset0:148 offset1:156
	ds_read2_b32 v[70:71], v44 offset0:181 offset1:189
	ds_read2_b32 v[72:73], v44 offset0:214 offset1:222
	ds_read2_b32 v[78:79], v44 offset0:247 offset1:255
	v_addc_co_u32_e32 v33, vcc, 0, v77, vcc
	global_store_dwordx4 v[32:33], v[28:31], off offset:2048 sc1
	v_add_co_u32_e32 v32, vcc, s57, v76
	v_or_b32_e32 v2, v27, v56
	s_waitcnt lgkmcnt(6)
	v_cvt_pk_bf16_f32 v28, v36, v34
	s_waitcnt lgkmcnt(4)
	v_cvt_pk_bf16_f32 v29, v38, v40
	s_waitcnt lgkmcnt(2)
	v_cvt_pk_bf16_f32 v30, v42, v70
	s_waitcnt lgkmcnt(0)
	v_cvt_pk_bf16_f32 v31, v72, v78
	v_addc_co_u32_e32 v33, vcc, 0, v77, vcc
	v_mul_u32_u24_e32 v2, 0x1600, v2
	global_store_dwordx4 v[32:33], v[28:31], off sc1
	v_lshl_add_u64 v[32:33], v[74:75], 0, v[2:3]
	s_nop 0
	v_cvt_pk_bf16_f32 v28, v37, v35
	v_cvt_pk_bf16_f32 v29, v39, v41
	v_cvt_pk_bf16_f32 v30, v43, v71
	v_cvt_pk_bf16_f32 v31, v73, v79
	global_store_dwordx4 v[32:33], v[28:31], off sc1
	s_waitcnt lgkmcnt(0)

.Ld1a_316:
	v_lshl_add_u64 v[70:71], v[42:43], 0, s[10:11]
	v_lshl_add_u64 v[72:73], v[40:41], 0, s[10:11]
	v_lshl_add_u64 v[74:75], v[38:39], 0, s[10:11]
	v_lshl_add_u64 v[76:77], v[36:37], 0, s[10:11]
	v_lshl_add_u64 v[78:79], v[34:35], 0, s[10:11]
	v_lshl_add_u64 v[80:81], v[32:33], 0, s[10:11]
	v_lshl_add_u64 v[82:83], v[30:31], 0, s[10:11]
	v_lshl_add_u64 v[84:85], v[28:29], 0, s[10:11]
	global_load_dword v100, v[70:71], off nt
	s_nop 0
	global_load_dword v101, v[72:73], off nt
	global_load_dword v102, v[74:75], off nt
	s_nop 0
	global_load_dword v103, v[76:77], off nt
	global_load_dword v104, v[78:79], off nt
	global_load_dword v105, v[80:81], off nt
	global_load_dword v106, v[82:83], off nt
	s_nop 0
	global_load_dword v107, v[84:85], off nt
	s_add_u32 s10, s10, 0x58000
	s_addc_u32 s11, s11, 0
	v_lshl_add_u64 v[70:71], v[42:43], 0, s[10:11]
	v_lshl_add_u64 v[72:73], v[40:41], 0, s[10:11]
	v_lshl_add_u64 v[74:75], v[38:39], 0, s[10:11]
	v_lshl_add_u64 v[76:77], v[36:37], 0, s[10:11]
	v_lshl_add_u64 v[78:79], v[34:35], 0, s[10:11]
	v_lshl_add_u64 v[80:81], v[32:33], 0, s[10:11]
	v_lshl_add_u64 v[82:83], v[30:31], 0, s[10:11]
	v_lshl_add_u64 v[84:85], v[28:29], 0, s[10:11]
	global_load_dword v108, v[70:71], off nt
	s_nop 0
	global_load_dword v109, v[72:73], off nt
	global_load_dword v110, v[74:75], off nt
	s_nop 0
	global_load_dword v111, v[76:77], off nt
	global_load_dword v112, v[78:79], off nt
	global_load_dword v113, v[80:81], off nt
	global_load_dword v114, v[82:83], off nt
	s_nop 0
	global_load_dword v115, v[84:85], off nt
	s_add_u32 s10, s10, 0x58000
	s_addc_u32 s11, s11, 0
	v_lshl_add_u64 v[70:71], v[42:43], 0, s[10:11]
	v_lshl_add_u64 v[72:73], v[40:41], 0, s[10:11]
	v_lshl_add_u64 v[74:75], v[38:39], 0, s[10:11]
	v_lshl_add_u64 v[76:77], v[36:37], 0, s[10:11]
	v_lshl_add_u64 v[78:79], v[34:35], 0, s[10:11]
	v_lshl_add_u64 v[80:81], v[32:33], 0, s[10:11]
	v_lshl_add_u64 v[82:83], v[30:31], 0, s[10:11]
	v_lshl_add_u64 v[84:85], v[28:29], 0, s[10:11]
	global_load_dword v116, v[70:71], off nt
	s_nop 0
	global_load_dword v117, v[72:73], off nt
	global_load_dword v118, v[74:75], off nt
	s_nop 0
	global_load_dword v119, v[76:77], off nt
	global_load_dword v120, v[78:79], off nt
	global_load_dword v121, v[80:81], off nt
	global_load_dword v122, v[82:83], off nt
	s_nop 0
	global_load_dword v123, v[84:85], off nt
	s_add_u32 s10, s10, 0x58000
	s_addc_u32 s11, s11, 0
	v_lshl_add_u64 v[70:71], v[42:43], 0, s[10:11]
	v_lshl_add_u64 v[72:73], v[40:41], 0, s[10:11]
	v_lshl_add_u64 v[74:75], v[38:39], 0, s[10:11]
	v_lshl_add_u64 v[76:77], v[36:37], 0, s[10:11]
	v_lshl_add_u64 v[78:79], v[34:35], 0, s[10:11]
	v_lshl_add_u64 v[80:81], v[32:33], 0, s[10:11]
	v_lshl_add_u64 v[82:83], v[30:31], 0, s[10:11]
	v_lshl_add_u64 v[84:85], v[28:29], 0, s[10:11]
	global_load_dword v124, v[70:71], off nt
	s_nop 0
	global_load_dword v125, v[72:73], off nt
	global_load_dword v126, v[74:75], off nt
	s_nop 0
	global_load_dword v127, v[76:77], off nt
	global_load_dword v128, v[78:79], off nt
	global_load_dword v129, v[80:81], off nt
	global_load_dword v130, v[82:83], off nt
	s_nop 0
	global_load_dword v131, v[84:85], off nt
	v_add_u32_e32 v132, 0x400, v2
	v_add_u32_e32 v133, 0x840, v2
	v_add_u32_e32 v134, 0xc40, v2
	v_add_u32_e32 v135, 0x1080, v2
	v_add_u32_e32 v136, 0x1480, v2
	v_add_u32_e32 v137, 0x18c0, v2
	v_add_u32_e32 v138, 0x1cc0, v2
	s_waitcnt vmcnt(30)
	ds_write2_b32 v2, v100, v101 offset1:66
	s_waitcnt vmcnt(28)
	ds_write2_b32 v2, v102, v103 offset0:132 offset1:198
	s_waitcnt vmcnt(26)
	ds_write2_b32 v132, v104, v105 offset0:8 offset1:74
	s_waitcnt vmcnt(24)
	ds_write2_b32 v132, v106, v107 offset0:140 offset1:206
	s_waitcnt vmcnt(22)
	ds_write2_b32 v133, v108, v109 offset1:66
	s_waitcnt vmcnt(20)
	ds_write2_b32 v133, v110, v111 offset0:132 offset1:198
	s_waitcnt vmcnt(18)
	ds_write2_b32 v134, v112, v113 offset0:8 offset1:74
	s_waitcnt vmcnt(16)
	ds_write2_b32 v134, v114, v115 offset0:140 offset1:206
	s_waitcnt vmcnt(14)
	ds_write2_b32 v135, v116, v117 offset1:66
	s_waitcnt vmcnt(12)
	ds_write2_b32 v135, v118, v119 offset0:132 offset1:198
	s_waitcnt vmcnt(10)
	ds_write2_b32 v136, v120, v121 offset0:8 offset1:74
	s_waitcnt vmcnt(8)
	ds_write2_b32 v136, v122, v123 offset0:140 offset1:206
	s_waitcnt vmcnt(6)
	ds_write2_b32 v137, v124, v125 offset1:66
	s_waitcnt vmcnt(4)
	ds_write2_b32 v137, v126, v127 offset0:132 offset1:198
	s_waitcnt vmcnt(2)
	ds_write2_b32 v138, v128, v129 offset0:8 offset1:74
	s_waitcnt vmcnt(0)
	ds_write2_b32 v138, v130, v131 offset0:140 offset1:206
	s_waitcnt lgkmcnt(0)
	v_or_b32_e32 v2, s0, v19
	v_cmp_lt_i32_e32 vcc, s44, v2
	ds_read2_b32 v[32:33], v44 offset0:33 offset1:41
	ds_read2_b32 v[34:35], v44 offset1:8
	ds_read2_b32 v[36:37], v44 offset0:66 offset1:74
	ds_read2_b32 v[38:39], v44 offset0:99 offset1:107
	ds_read2_b32 v[40:41], v44 offset0:132 offset1:140
	ds_read2_b32 v[42:43], v44 offset0:165 offset1:173
	ds_read2_b32 v[70:71], v44 offset0:198 offset1:206
	ds_read2_b32 v[72:73], v44 offset0:231 offset1:239
	v_cndmask_b32_e32 v27, 0, v67, vcc
	s_waitcnt lgkmcnt(6)
	v_cvt_pk_bf16_f32 v28, v34, v32
	v_add_lshl_u32 v27, v27, v2, 1
	v_lshlrev_b32_e32 v2, 2, v2
	v_bitop3_b32 v34, s0, v69, v19 bitop3:0xc8
	v_and_b32_e32 v27, 0xffffff00, v27
	v_cndmask_b32_e32 v32, 0, v68, vcc
	v_and_or_b32 v2, v2, 16, v34
	v_or3_b32 v76, v2, v32, v27
	v_or_b32_e32 v2, s0, v45
	v_ashrrev_i32_e32 v77, 31, v76
	v_cmp_lt_i32_e32 vcc, s44, v2
	v_lshl_add_u64 v[74:75], s[8:9], 1, v[10:11]
	v_lshlrev_b64 v[76:77], 11, v[76:77]
	v_cndmask_b32_e32 v27, 0, v67, vcc
	s_waitcnt lgkmcnt(4)
	v_cvt_pk_bf16_f32 v29, v36, v38
	s_waitcnt lgkmcnt(2)
	v_cvt_pk_bf16_f32 v30, v40, v42
	s_waitcnt lgkmcnt(0)
	v_cvt_pk_bf16_f32 v31, v70, v72
	v_lshl_add_u64 v[76:77], v[74:75], 0, v[76:77]
	v_add_lshl_u32 v27, v27, v2, 1
	v_lshlrev_b32_e32 v2, 2, v2
	global_store_dwordx4 v[76:77], v[28:31], off sc1
	v_cndmask_b32_e32 v32, 0, v68, vcc
	v_and_b32_e32 v2, 16, v2
	v_cvt_pk_bf16_f32 v28, v35, v33
	v_bitop3_b32 v33, s0, v69, v45 bitop3:0xc8
	v_and_b32_e32 v27, 0xffffff00, v27
	v_or3_b32 v2, v33, v2, v32
	v_or3_b32 v32, v2, v27, 4
	v_or_b32_e32 v2, s0, v46
	v_ashrrev_i32_e32 v33, 31, v32
	v_cmp_lt_i32_e32 vcc, s44, v2
	v_lshlrev_b64 v[32:33], 11, v[32:33]
	v_cvt_pk_bf16_f32 v29, v37, v39
	v_cndmask_b32_e32 v27, 0, v67, vcc
	v_cvt_pk_bf16_f32 v30, v41, v43
	v_cvt_pk_bf16_f32 v31, v71, v73
	v_lshl_add_u64 v[32:33], v[74:75], 0, v[32:33]
	v_add_lshl_u32 v27, v27, v2, 1
	v_lshlrev_b32_e32 v2, 2, v2
	ds_read2_b32 v[34:35], v44 offset0:16 offset1:24
	ds_read2_b32 v[36:37], v44 offset0:49 offset1:57
	ds_read2_b32 v[38:39], v44 offset0:82 offset1:90
	ds_read2_b32 v[40:41], v44 offset0:115 offset1:123
	ds_read2_b32 v[42:43], v44 offset0:148 offset1:156
	ds_read2_b32 v[70:71], v44 offset0:181 offset1:189
	ds_read2_b32 v[72:73], v44 offset0:214 offset1:222
	ds_read2_b32 v[76:77], v44 offset0:247 offset1:255
	global_store_dwordx4 v[32:33], v[28:31], off sc1
	v_cndmask_b32_e32 v32, 0, v68, vcc
	v_and_b32_e32 v2, 16, v2
	v_bitop3_b32 v33, s0, v69, v46 bitop3:0xc8
	v_and_b32_e32 v27, 0xffffff00, v27
	v_or3_b32 v2, v33, v2, v32
	v_or3_b32 v32, v2, v27, 8
	v_or_b32_e32 v2, s0, v47
	v_ashrrev_i32_e32 v33, 31, v32
	v_cmp_lt_i32_e32 vcc, s44, v2
	v_lshlrev_b64 v[32:33], 11, v[32:33]
	s_waitcnt lgkmcnt(6)
	v_cvt_pk_bf16_f32 v28, v34, v36
	v_cndmask_b32_e32 v27, 0, v67, vcc
	s_waitcnt lgkmcnt(4)
	v_cvt_pk_bf16_f32 v29, v38, v40
	s_waitcnt lgkmcnt(2)
	v_cvt_pk_bf16_f32 v30, v42, v70
	s_waitcnt lgkmcnt(0)
	v_cvt_pk_bf16_f32 v31, v72, v76
	v_lshl_add_u64 v[32:33], v[74:75], 0, v[32:33]
	v_add_lshl_u32 v27, v27, v2, 1
	v_lshlrev_b32_e32 v2, 2, v2
	global_store_dwordx4 v[32:33], v[28:31], off sc1
	v_and_b32_e32 v2, 16, v2
	v_and_b32_e32 v27, 0xffffff00, v27
	v_cndmask_b32_e32 v28, 0, v68, vcc
	v_bitop3_b32 v29, s0, v69, v47 bitop3:0xc8
	v_or3_b32 v2, v29, v2, v28
	v_or3_b32 v32, v2, v27, 12
	v_ashrrev_i32_e32 v33, 31, v32
	v_lshlrev_b64 v[32:33], 11, v[32:33]
	v_cvt_pk_bf16_f32 v28, v35, v37
	v_cvt_pk_bf16_f32 v29, v39, v41
	v_cvt_pk_bf16_f32 v30, v43, v71
	v_cvt_pk_bf16_f32 v31, v73, v77
	v_lshl_add_u64 v[32:33], v[74:75], 0, v[32:33]
	global_store_dwordx4 v[32:33], v[28:31], off sc1
	s_waitcnt lgkmcnt(0)
	s_branch .Ld1a_267
